# K-loop alignment padding is branched over instead of executed
# baseline (speedup 1.0000x reference)
.LBB0_60:
	s_or_b64 exec, exec, s[10:11]
	v_mov_b32_e32 v2, s8
	s_waitcnt lgkmcnt(0)
	s_barrier
	ds_read_b32 v2, v2
	s_waitcnt lgkmcnt(0)
	v_readfirstlane_b32 s2, v2
	s_ashr_i32 s10, s2, 3
	s_and_b32 s10, s10, -8
	s_or_b32 s12, s10, s48
	s_cmp_gt_i32 s12, 39
	s_mov_b64 s[10:11], -1
	s_cbranch_scc1 .LBB0_55
	s_lshl_b32 s11, s2, 7
	s_lshl_b32 s10, s12, 10
	s_and_b32 s11, s11, 0x380
	s_or_b32 s13, s10, s11
	s_bfe_u32 s12, s2, 0x30003
	s_lshl_b32 s49, s12, 7
	s_mul_i32 s10, s13, 0x1820
	s_mul_hi_i32 s2, s13, 0x1820
	s_add_u32 s10, s34, s10
	s_addc_u32 s11, s35, s2
	s_lshl_b32 s2, s12, 18
	v_readlane_b32 s42, v246, 23
	s_add_u32 s42, s42, s2
	v_readlane_b32 s43, v246, 24
	v_readfirstlane_b32 s56, v1
	v_add_u32_e32 v6, 0x4000, v1
	s_waitcnt lgkmcnt(0)
	s_barrier
	s_addc_u32 s43, s43, 0
	v_lshl_add_u64 v[2:3], v[66:67], 1, s[10:11]
	s_mov_b32 m0, s56
	v_readfirstlane_b32 s57, v6
	v_add_u32_e32 v8, 0x1000, v1
	global_load_lds_dwordx4 v[2:3], off
	v_lshl_add_u64 v[4:5], v[68:69], 1, s[42:43]
	s_mov_b32 m0, s57
	v_readfirstlane_b32 s58, v8
	v_add_u32_e32 v10, 0x5000, v1
	global_load_lds_dwordx4 v[4:5], off
	v_lshl_add_u64 v[6:7], v[70:71], 1, s[10:11]
	s_mov_b32 m0, s58
	v_readfirstlane_b32 s59, v10
	v_add_u32_e32 v12, 0x2000, v1
	global_load_lds_dwordx4 v[6:7], off
	v_lshl_add_u64 v[8:9], v[72:73], 1, s[42:43]
	s_mov_b32 m0, s59
	v_readfirstlane_b32 s60, v12
	v_add_u32_e32 v14, 0x6000, v1
	global_load_lds_dwordx4 v[8:9], off
	v_lshl_add_u64 v[10:11], v[74:75], 1, s[10:11]
	s_mov_b32 m0, s60
	v_readfirstlane_b32 s61, v14
	v_add_u32_e32 v16, 0x3000, v1
	global_load_lds_dwordx4 v[10:11], off
	v_lshl_add_u64 v[12:13], v[76:77], 1, s[42:43]
	s_mov_b32 m0, s61
	v_readfirstlane_b32 s97, v16
	v_add_u32_e32 v18, 0x7000, v1
	global_load_lds_dwordx4 v[12:13], off
	v_lshl_add_u64 v[14:15], v[78:79], 1, s[10:11]
	s_mov_b32 m0, s97
	v_readfirstlane_b32 s44, v18
	global_load_lds_dwordx4 v[14:15], off
	v_lshl_add_u64 v[16:17], v[80:81], 1, s[42:43]
	s_mov_b32 m0, s44
	v_add_u32_e32 v20, 0x8000, v1
	global_load_lds_dwordx4 v[16:17], off
	s_waitcnt vmcnt(0)
	v_readfirstlane_b32 s42, v20
	v_add_u32_e32 v20, 0xc000, v1
	s_waitcnt lgkmcnt(0)
	s_barrier
	v_lshl_add_u64 v[18:19], v[2:3], 0, s[98:99]
	s_mov_b32 m0, s42
	v_readfirstlane_b32 s43, v20
	v_add_u32_e32 v20, 0x9000, v1
	global_load_lds_dwordx4 v[18:19], off
	v_lshl_add_u64 v[18:19], v[4:5], 0, s[98:99]
	s_mov_b32 m0, s43
	v_readfirstlane_b32 s50, v20
	v_add_u32_e32 v20, 0xd000, v1
	global_load_lds_dwordx4 v[18:19], off
	v_lshl_add_u64 v[18:19], v[6:7], 0, s[98:99]
	s_mov_b32 m0, s50
	v_readfirstlane_b32 s51, v20
	v_add_u32_e32 v20, 0xa000, v1
	global_load_lds_dwordx4 v[18:19], off
	v_lshl_add_u64 v[18:19], v[8:9], 0, s[98:99]
	s_mov_b32 m0, s51
	v_readfirstlane_b32 s52, v20
	v_add_u32_e32 v20, 0xe000, v1
	global_load_lds_dwordx4 v[18:19], off
	v_lshl_add_u64 v[18:19], v[10:11], 0, s[98:99]
	s_mov_b32 m0, s52
	v_readfirstlane_b32 s53, v20
	v_add_u32_e32 v20, 0xb000, v1
	global_load_lds_dwordx4 v[18:19], off
	v_lshl_add_u64 v[18:19], v[12:13], 0, s[98:99]
	s_mov_b32 m0, s53
	v_readfirstlane_b32 s54, v20
	v_add_u32_e32 v20, 0xf000, v1
	global_load_lds_dwordx4 v[18:19], off
	v_lshl_add_u64 v[18:19], v[14:15], 0, s[98:99]
	s_mov_b32 m0, s54
	v_readfirstlane_b32 s55, v20
	global_load_lds_dwordx4 v[18:19], off
	v_lshl_add_u64 v[18:19], v[16:17], 0, s[98:99]
	s_mov_b32 m0, s55
	s_mov_b64 vcc, 0x100
	global_load_lds_dwordx4 v[18:19], off
	v_add_u32_e32 v19, v102, v104
	ds_read_b128 v[20:23], v19 offset:16384
	ds_read_b128 v[32:35], v19 offset:18432
	ds_read_b128 v[40:43], v19 offset:20480
	ds_read_b128 v[126:129], v19 offset:19456
	ds_read_b128 v[48:51], v19 offset:22528
	ds_read_b128 v[130:133], v19 offset:21504
	v_add_u32_e32 v18, v102, v103
	ds_read_b128 v[24:27], v18
	ds_read_b128 v[52:55], v18 offset:2048
	ds_read_b128 v[98:101], v18 offset:4096
	ds_read_b128 v[118:121], v18 offset:6144
	ds_read_b128 v[122:125], v19 offset:17408
	ds_read_b128 v[134:137], v19 offset:23552
	s_waitcnt lgkmcnt(0)
	v_mfma_f32_16x16x32_bf16 v[28:31], v[20:23], v[24:27], 0
	v_lshl_add_u64 v[64:65], v[2:3], 0, vcc
	s_mov_b32 m0, s56
	s_mov_b64 s[62:63], 0x180
	v_mfma_f32_16x16x32_bf16 v[36:39], v[32:35], v[24:27], 0
	v_mfma_f32_16x16x32_bf16 v[44:47], v[40:43], v[24:27], 0
	v_mfma_f32_16x16x32_bf16 v[24:27], v[48:51], v[24:27], 0
	v_mfma_f32_16x16x32_bf16 v[56:59], v[20:23], v[52:55], 0
	v_mfma_f32_16x16x32_bf16 v[60:63], v[32:35], v[52:55], 0
	v_mfma_f32_16x16x32_bf16 v[94:97], v[40:43], v[52:55], 0
	v_mfma_f32_16x16x32_bf16 v[52:55], v[48:51], v[52:55], 0
	v_mfma_f32_16x16x32_bf16 v[106:109], v[20:23], v[98:101], 0
	v_mfma_f32_16x16x32_bf16 v[110:113], v[32:35], v[98:101], 0
	v_mfma_f32_16x16x32_bf16 v[114:117], v[40:43], v[98:101], 0
	v_mfma_f32_16x16x32_bf16 v[98:101], v[48:51], v[98:101], 0
	v_mfma_f32_16x16x32_bf16 v[20:23], v[20:23], v[118:121], 0
	v_mfma_f32_16x16x32_bf16 v[32:35], v[32:35], v[118:121], 0
	v_mfma_f32_16x16x32_bf16 v[40:43], v[40:43], v[118:121], 0
	v_mfma_f32_16x16x32_bf16 v[48:51], v[48:51], v[118:121], 0
	ds_read_b128 v[118:121], v18 offset:1024
	s_waitcnt lgkmcnt(0)
	v_mfma_f32_16x16x32_bf16 v[28:31], v[122:125], v[118:121], v[28:31]
	v_mfma_f32_16x16x32_bf16 v[36:39], v[126:129], v[118:121], v[36:39]
	v_mfma_f32_16x16x32_bf16 v[44:47], v[130:133], v[118:121], v[44:47]
	v_mfma_f32_16x16x32_bf16 v[24:27], v[134:137], v[118:121], v[24:27]
	ds_read_b128 v[118:121], v18 offset:3072
	s_waitcnt lgkmcnt(0)
	v_mfma_f32_16x16x32_bf16 v[56:59], v[122:125], v[118:121], v[56:59]
	v_mfma_f32_16x16x32_bf16 v[60:63], v[126:129], v[118:121], v[60:63]
	v_mfma_f32_16x16x32_bf16 v[94:97], v[130:133], v[118:121], v[94:97]
	v_mfma_f32_16x16x32_bf16 v[52:55], v[134:137], v[118:121], v[52:55]
	ds_read_b128 v[118:121], v18 offset:5120
	s_waitcnt lgkmcnt(0)
	v_mfma_f32_16x16x32_bf16 v[106:109], v[122:125], v[118:121], v[106:109]
	v_mfma_f32_16x16x32_bf16 v[110:113], v[126:129], v[118:121], v[110:113]
	v_mfma_f32_16x16x32_bf16 v[114:117], v[130:133], v[118:121], v[114:117]
	v_mfma_f32_16x16x32_bf16 v[98:101], v[134:137], v[118:121], v[98:101]
	ds_read_b128 v[118:121], v18 offset:7168
	s_waitcnt vmcnt(0)
	s_waitcnt lgkmcnt(0)
	s_barrier
	global_load_lds_dwordx4 v[64:65], off
	v_lshl_add_u64 v[64:65], v[4:5], 0, vcc
	s_mov_b32 m0, s57
	s_waitcnt lgkmcnt(0)
	v_mfma_f32_16x16x32_bf16 v[20:23], v[122:125], v[118:121], v[20:23]
	global_load_lds_dwordx4 v[64:65], off
	v_lshl_add_u64 v[64:65], v[6:7], 0, vcc
	s_mov_b32 m0, s58
	v_mfma_f32_16x16x32_bf16 v[32:35], v[126:129], v[118:121], v[32:35]
	global_load_lds_dwordx4 v[64:65], off
	v_lshl_add_u64 v[64:65], v[8:9], 0, vcc
	s_mov_b32 m0, s59
	v_mfma_f32_16x16x32_bf16 v[40:43], v[130:133], v[118:121], v[40:43]
	global_load_lds_dwordx4 v[64:65], off
	v_lshl_add_u64 v[64:65], v[10:11], 0, vcc
	s_mov_b32 m0, s60
	v_mfma_f32_16x16x32_bf16 v[48:51], v[134:137], v[118:121], v[48:51]
	global_load_lds_dwordx4 v[64:65], off
	v_lshl_add_u64 v[64:65], v[12:13], 0, vcc
	s_mov_b32 m0, s61
	s_nop 0
	global_load_lds_dwordx4 v[64:65], off
	v_lshl_add_u64 v[64:65], v[14:15], 0, vcc
	s_mov_b32 m0, s97
	s_nop 0
	global_load_lds_dwordx4 v[64:65], off
	v_lshl_add_u64 v[64:65], v[16:17], 0, vcc
	s_mov_b32 m0, s44
	s_nop 0
	global_load_lds_dwordx4 v[64:65], off
	ds_read_b128 v[122:125], v19 offset:49152
	ds_read_b128 v[118:121], v18 offset:32768
	ds_read_b128 v[126:129], v19 offset:51200
	ds_read_b128 v[130:133], v19 offset:53248
	ds_read_b128 v[134:137], v19 offset:55296
	s_waitcnt lgkmcnt(0)
	v_mfma_f32_16x16x32_bf16 v[28:31], v[122:125], v[118:121], v[28:31]
	v_lshl_add_u64 v[64:65], v[2:3], 0, s[62:63]
	s_mov_b32 m0, s42
	v_mfma_f32_16x16x32_bf16 v[36:39], v[126:129], v[118:121], v[36:39]
	v_mfma_f32_16x16x32_bf16 v[44:47], v[130:133], v[118:121], v[44:47]
	v_mfma_f32_16x16x32_bf16 v[24:27], v[134:137], v[118:121], v[24:27]
	ds_read_b128 v[118:121], v18 offset:34816
	s_waitcnt lgkmcnt(0)
	v_mfma_f32_16x16x32_bf16 v[56:59], v[122:125], v[118:121], v[56:59]
	v_mfma_f32_16x16x32_bf16 v[60:63], v[126:129], v[118:121], v[60:63]
	v_mfma_f32_16x16x32_bf16 v[94:97], v[130:133], v[118:121], v[94:97]
	v_mfma_f32_16x16x32_bf16 v[52:55], v[134:137], v[118:121], v[52:55]
	ds_read_b128 v[118:121], v18 offset:36864
	s_waitcnt lgkmcnt(0)
	v_mfma_f32_16x16x32_bf16 v[106:109], v[122:125], v[118:121], v[106:109]
	v_mfma_f32_16x16x32_bf16 v[110:113], v[126:129], v[118:121], v[110:113]
	v_mfma_f32_16x16x32_bf16 v[114:117], v[130:133], v[118:121], v[114:117]
	v_mfma_f32_16x16x32_bf16 v[98:101], v[134:137], v[118:121], v[98:101]
	ds_read_b128 v[118:121], v18 offset:38912
	s_waitcnt lgkmcnt(0)
	v_mfma_f32_16x16x32_bf16 v[20:23], v[122:125], v[118:121], v[20:23]
	ds_read_b128 v[122:125], v19 offset:50176
	v_mfma_f32_16x16x32_bf16 v[32:35], v[126:129], v[118:121], v[32:35]
	ds_read_b128 v[126:129], v19 offset:52224
	v_mfma_f32_16x16x32_bf16 v[40:43], v[130:133], v[118:121], v[40:43]
	ds_read_b128 v[130:133], v19 offset:54272
	v_mfma_f32_16x16x32_bf16 v[48:51], v[134:137], v[118:121], v[48:51]
	ds_read_b128 v[134:137], v19 offset:56320
	ds_read_b128 v[118:121], v18 offset:33792
	s_waitcnt lgkmcnt(0)
	v_mfma_f32_16x16x32_bf16 v[28:31], v[122:125], v[118:121], v[28:31]
	v_mfma_f32_16x16x32_bf16 v[36:39], v[126:129], v[118:121], v[36:39]
	v_mfma_f32_16x16x32_bf16 v[44:47], v[130:133], v[118:121], v[44:47]
	v_mfma_f32_16x16x32_bf16 v[24:27], v[134:137], v[118:121], v[24:27]
	ds_read_b128 v[118:121], v18 offset:35840
	s_waitcnt lgkmcnt(0)
	v_mfma_f32_16x16x32_bf16 v[56:59], v[122:125], v[118:121], v[56:59]
	v_mfma_f32_16x16x32_bf16 v[60:63], v[126:129], v[118:121], v[60:63]
	v_mfma_f32_16x16x32_bf16 v[94:97], v[130:133], v[118:121], v[94:97]
	v_mfma_f32_16x16x32_bf16 v[52:55], v[134:137], v[118:121], v[52:55]
	ds_read_b128 v[118:121], v18 offset:37888
	s_waitcnt lgkmcnt(0)
	v_mfma_f32_16x16x32_bf16 v[106:109], v[122:125], v[118:121], v[106:109]
	v_mfma_f32_16x16x32_bf16 v[110:113], v[126:129], v[118:121], v[110:113]
	v_mfma_f32_16x16x32_bf16 v[114:117], v[130:133], v[118:121], v[114:117]
	v_mfma_f32_16x16x32_bf16 v[98:101], v[134:137], v[118:121], v[98:101]
	ds_read_b128 v[118:121], v18 offset:39936
	s_waitcnt vmcnt(0)
	s_waitcnt lgkmcnt(0)
	s_barrier
	global_load_lds_dwordx4 v[64:65], off
	v_lshl_add_u64 v[64:65], v[4:5], 0, s[62:63]
	s_mov_b32 m0, s43
	s_waitcnt lgkmcnt(0)
	v_mfma_f32_16x16x32_bf16 v[20:23], v[122:125], v[118:121], v[20:23]
	global_load_lds_dwordx4 v[64:65], off
	v_lshl_add_u64 v[64:65], v[6:7], 0, s[62:63]
	s_mov_b32 m0, s50
	v_mfma_f32_16x16x32_bf16 v[32:35], v[126:129], v[118:121], v[32:35]
	global_load_lds_dwordx4 v[64:65], off
	v_lshl_add_u64 v[64:65], v[8:9], 0, s[62:63]
	s_mov_b32 m0, s51
	v_mfma_f32_16x16x32_bf16 v[40:43], v[130:133], v[118:121], v[40:43]
	global_load_lds_dwordx4 v[64:65], off
	v_lshl_add_u64 v[64:65], v[10:11], 0, s[62:63]
	s_mov_b32 m0, s52
	v_mfma_f32_16x16x32_bf16 v[48:51], v[134:137], v[118:121], v[48:51]
	global_load_lds_dwordx4 v[64:65], off
	v_lshl_add_u64 v[64:65], v[12:13], 0, s[62:63]
	s_mov_b32 m0, s53
	s_nop 0
	global_load_lds_dwordx4 v[64:65], off
	v_lshl_add_u64 v[64:65], v[14:15], 0, s[62:63]
	s_mov_b32 m0, s54
	s_nop 0
	global_load_lds_dwordx4 v[64:65], off
	v_lshl_add_u64 v[64:65], v[16:17], 0, s[62:63]
	s_mov_b32 m0, s55
	s_nop 0
	global_load_lds_dwordx4 v[64:65], off
	ds_read_b128 v[122:125], v19 offset:16384
	ds_read_b128 v[118:121], v18
	ds_read_b128 v[126:129], v19 offset:18432
	ds_read_b128 v[130:133], v19 offset:20480
	ds_read_b128 v[134:137], v19 offset:22528
	s_waitcnt lgkmcnt(0)
	v_mfma_f32_16x16x32_bf16 v[28:31], v[122:125], v[118:121], v[28:31]
	v_lshl_add_u64 v[64:65], v[2:3], 0, s[94:95]
	s_mov_b32 m0, s56
	v_mfma_f32_16x16x32_bf16 v[36:39], v[126:129], v[118:121], v[36:39]
	v_mfma_f32_16x16x32_bf16 v[44:47], v[130:133], v[118:121], v[44:47]
	v_mfma_f32_16x16x32_bf16 v[24:27], v[134:137], v[118:121], v[24:27]
	ds_read_b128 v[118:121], v18 offset:2048
	s_waitcnt lgkmcnt(0)
	v_mfma_f32_16x16x32_bf16 v[56:59], v[122:125], v[118:121], v[56:59]
	v_mfma_f32_16x16x32_bf16 v[60:63], v[126:129], v[118:121], v[60:63]
	v_mfma_f32_16x16x32_bf16 v[94:97], v[130:133], v[118:121], v[94:97]
	v_mfma_f32_16x16x32_bf16 v[52:55], v[134:137], v[118:121], v[52:55]
	ds_read_b128 v[118:121], v18 offset:4096
	s_waitcnt lgkmcnt(0)
	v_mfma_f32_16x16x32_bf16 v[106:109], v[122:125], v[118:121], v[106:109]
	v_mfma_f32_16x16x32_bf16 v[110:113], v[126:129], v[118:121], v[110:113]
	v_mfma_f32_16x16x32_bf16 v[114:117], v[130:133], v[118:121], v[114:117]
	v_mfma_f32_16x16x32_bf16 v[98:101], v[134:137], v[118:121], v[98:101]
	ds_read_b128 v[118:121], v18 offset:6144
	s_waitcnt lgkmcnt(0)
	v_mfma_f32_16x16x32_bf16 v[20:23], v[122:125], v[118:121], v[20:23]
	ds_read_b128 v[122:125], v19 offset:17408
	v_mfma_f32_16x16x32_bf16 v[32:35], v[126:129], v[118:121], v[32:35]
	ds_read_b128 v[126:129], v19 offset:19456
	v_mfma_f32_16x16x32_bf16 v[40:43], v[130:133], v[118:121], v[40:43]
	ds_read_b128 v[130:133], v19 offset:21504
	v_mfma_f32_16x16x32_bf16 v[48:51], v[134:137], v[118:121], v[48:51]
	ds_read_b128 v[134:137], v19 offset:23552
	ds_read_b128 v[118:121], v18 offset:1024
	s_waitcnt lgkmcnt(0)
	v_mfma_f32_16x16x32_bf16 v[28:31], v[122:125], v[118:121], v[28:31]
	v_mfma_f32_16x16x32_bf16 v[36:39], v[126:129], v[118:121], v[36:39]
	v_mfma_f32_16x16x32_bf16 v[44:47], v[130:133], v[118:121], v[44:47]
	v_mfma_f32_16x16x32_bf16 v[24:27], v[134:137], v[118:121], v[24:27]
	ds_read_b128 v[118:121], v18 offset:3072
	s_waitcnt lgkmcnt(0)
	v_mfma_f32_16x16x32_bf16 v[56:59], v[122:125], v[118:121], v[56:59]
	v_mfma_f32_16x16x32_bf16 v[60:63], v[126:129], v[118:121], v[60:63]
	v_mfma_f32_16x16x32_bf16 v[94:97], v[130:133], v[118:121], v[94:97]
	v_mfma_f32_16x16x32_bf16 v[52:55], v[134:137], v[118:121], v[52:55]
	ds_read_b128 v[118:121], v18 offset:5120
	s_waitcnt lgkmcnt(0)
	v_mfma_f32_16x16x32_bf16 v[106:109], v[122:125], v[118:121], v[106:109]
	v_mfma_f32_16x16x32_bf16 v[110:113], v[126:129], v[118:121], v[110:113]
	v_mfma_f32_16x16x32_bf16 v[114:117], v[130:133], v[118:121], v[114:117]
	v_mfma_f32_16x16x32_bf16 v[98:101], v[134:137], v[118:121], v[98:101]
	ds_read_b128 v[118:121], v18 offset:7168
	s_waitcnt vmcnt(0)
	s_waitcnt lgkmcnt(0)
	s_barrier
	global_load_lds_dwordx4 v[64:65], off
	v_lshl_add_u64 v[64:65], v[4:5], 0, s[94:95]
	s_mov_b32 m0, s57
	s_waitcnt lgkmcnt(0)
	v_mfma_f32_16x16x32_bf16 v[20:23], v[122:125], v[118:121], v[20:23]
	global_load_lds_dwordx4 v[64:65], off
	v_lshl_add_u64 v[64:65], v[6:7], 0, s[94:95]
	s_mov_b32 m0, s58
	v_mfma_f32_16x16x32_bf16 v[32:35], v[126:129], v[118:121], v[32:35]
	global_load_lds_dwordx4 v[64:65], off
	v_lshl_add_u64 v[64:65], v[8:9], 0, s[94:95]
	s_mov_b32 m0, s59
	v_mfma_f32_16x16x32_bf16 v[40:43], v[130:133], v[118:121], v[40:43]
	global_load_lds_dwordx4 v[64:65], off
	v_lshl_add_u64 v[64:65], v[10:11], 0, s[94:95]
	s_mov_b32 m0, s60
	v_mfma_f32_16x16x32_bf16 v[48:51], v[134:137], v[118:121], v[48:51]
	global_load_lds_dwordx4 v[64:65], off
	v_lshl_add_u64 v[64:65], v[12:13], 0, s[94:95]
	s_mov_b32 m0, s61
	s_nop 0
	global_load_lds_dwordx4 v[64:65], off
	v_lshl_add_u64 v[64:65], v[14:15], 0, s[94:95]
	s_mov_b32 m0, s97
	s_nop 0
	global_load_lds_dwordx4 v[64:65], off
	v_lshl_add_u64 v[64:65], v[16:17], 0, s[94:95]
	s_mov_b32 m0, s44
	s_nop 0
	global_load_lds_dwordx4 v[64:65], off
	ds_read_b128 v[122:125], v19 offset:49152
	ds_read_b128 v[118:121], v18 offset:32768
	ds_read_b128 v[126:129], v19 offset:51200
	ds_read_b128 v[130:133], v19 offset:53248
	ds_read_b128 v[134:137], v19 offset:55296
	s_waitcnt lgkmcnt(0)
	v_mfma_f32_16x16x32_bf16 v[28:31], v[122:125], v[118:121], v[28:31]
	v_lshl_add_u64 v[64:65], v[2:3], 0, s[36:37]
	s_mov_b32 m0, s42
	v_mfma_f32_16x16x32_bf16 v[36:39], v[126:129], v[118:121], v[36:39]
	v_mfma_f32_16x16x32_bf16 v[44:47], v[130:133], v[118:121], v[44:47]
	v_mfma_f32_16x16x32_bf16 v[24:27], v[134:137], v[118:121], v[24:27]
	ds_read_b128 v[118:121], v18 offset:34816
	s_waitcnt lgkmcnt(0)
	v_mfma_f32_16x16x32_bf16 v[56:59], v[122:125], v[118:121], v[56:59]
	v_mfma_f32_16x16x32_bf16 v[60:63], v[126:129], v[118:121], v[60:63]
	v_mfma_f32_16x16x32_bf16 v[94:97], v[130:133], v[118:121], v[94:97]
	v_mfma_f32_16x16x32_bf16 v[52:55], v[134:137], v[118:121], v[52:55]
	ds_read_b128 v[118:121], v18 offset:36864
	s_waitcnt lgkmcnt(0)
	v_mfma_f32_16x16x32_bf16 v[106:109], v[122:125], v[118:121], v[106:109]
	v_mfma_f32_16x16x32_bf16 v[110:113], v[126:129], v[118:121], v[110:113]
	v_mfma_f32_16x16x32_bf16 v[114:117], v[130:133], v[118:121], v[114:117]
	v_mfma_f32_16x16x32_bf16 v[98:101], v[134:137], v[118:121], v[98:101]
	ds_read_b128 v[118:121], v18 offset:38912
	s_waitcnt lgkmcnt(0)
	v_mfma_f32_16x16x32_bf16 v[20:23], v[122:125], v[118:121], v[20:23]
	ds_read_b128 v[122:125], v19 offset:50176
	v_mfma_f32_16x16x32_bf16 v[32:35], v[126:129], v[118:121], v[32:35]
	ds_read_b128 v[126:129], v19 offset:52224
	v_mfma_f32_16x16x32_bf16 v[40:43], v[130:133], v[118:121], v[40:43]
	ds_read_b128 v[130:133], v19 offset:54272
	v_mfma_f32_16x16x32_bf16 v[48:51], v[134:137], v[118:121], v[48:51]
	ds_read_b128 v[134:137], v19 offset:56320
	ds_read_b128 v[118:121], v18 offset:33792
	s_waitcnt lgkmcnt(0)
	v_mfma_f32_16x16x32_bf16 v[28:31], v[122:125], v[118:121], v[28:31]
	v_mfma_f32_16x16x32_bf16 v[36:39], v[126:129], v[118:121], v[36:39]
	v_mfma_f32_16x16x32_bf16 v[44:47], v[130:133], v[118:121], v[44:47]
	v_mfma_f32_16x16x32_bf16 v[24:27], v[134:137], v[118:121], v[24:27]
	ds_read_b128 v[118:121], v18 offset:35840
	s_waitcnt lgkmcnt(0)
	v_mfma_f32_16x16x32_bf16 v[56:59], v[122:125], v[118:121], v[56:59]
	v_mfma_f32_16x16x32_bf16 v[60:63], v[126:129], v[118:121], v[60:63]
	v_mfma_f32_16x16x32_bf16 v[94:97], v[130:133], v[118:121], v[94:97]
	v_mfma_f32_16x16x32_bf16 v[52:55], v[134:137], v[118:121], v[52:55]
	ds_read_b128 v[118:121], v18 offset:37888
	s_waitcnt lgkmcnt(0)
	v_mfma_f32_16x16x32_bf16 v[106:109], v[122:125], v[118:121], v[106:109]
	v_mfma_f32_16x16x32_bf16 v[110:113], v[126:129], v[118:121], v[110:113]
	v_mfma_f32_16x16x32_bf16 v[114:117], v[130:133], v[118:121], v[114:117]
	v_mfma_f32_16x16x32_bf16 v[98:101], v[134:137], v[118:121], v[98:101]
	ds_read_b128 v[118:121], v18 offset:39936
	s_waitcnt vmcnt(0)
	s_waitcnt lgkmcnt(0)
	s_barrier
	global_load_lds_dwordx4 v[64:65], off
	v_lshl_add_u64 v[64:65], v[4:5], 0, s[36:37]
	s_mov_b32 m0, s43
	s_waitcnt lgkmcnt(0)
	v_mfma_f32_16x16x32_bf16 v[20:23], v[122:125], v[118:121], v[20:23]
	global_load_lds_dwordx4 v[64:65], off
	v_lshl_add_u64 v[64:65], v[6:7], 0, s[36:37]
	s_mov_b32 m0, s50
	v_mfma_f32_16x16x32_bf16 v[32:35], v[126:129], v[118:121], v[32:35]
	global_load_lds_dwordx4 v[64:65], off
	v_lshl_add_u64 v[64:65], v[8:9], 0, s[36:37]
	s_mov_b32 m0, s51
	v_mfma_f32_16x16x32_bf16 v[40:43], v[130:133], v[118:121], v[40:43]
	global_load_lds_dwordx4 v[64:65], off
	v_lshl_add_u64 v[64:65], v[10:11], 0, s[36:37]
	s_mov_b32 m0, s52
	v_mfma_f32_16x16x32_bf16 v[48:51], v[134:137], v[118:121], v[48:51]
	global_load_lds_dwordx4 v[64:65], off
	v_lshl_add_u64 v[64:65], v[12:13], 0, s[36:37]
	s_mov_b32 m0, s53
	s_nop 0
	global_load_lds_dwordx4 v[64:65], off
	v_lshl_add_u64 v[64:65], v[14:15], 0, s[36:37]
	s_mov_b32 m0, s54
	s_nop 0
	global_load_lds_dwordx4 v[64:65], off
	v_lshl_add_u64 v[64:65], v[16:17], 0, s[36:37]
	s_mov_b32 m0, s55
	s_nop 0
	global_load_lds_dwordx4 v[64:65], off
	ds_read_b128 v[122:125], v19 offset:16384
	ds_read_b128 v[118:121], v18
	ds_read_b128 v[126:129], v19 offset:18432
	ds_read_b128 v[130:133], v19 offset:20480
	ds_read_b128 v[134:137], v19 offset:22528
	s_waitcnt lgkmcnt(0)
	v_mfma_f32_16x16x32_bf16 v[28:31], v[122:125], v[118:121], v[28:31]
	v_lshl_add_u64 v[64:65], v[2:3], 0, s[22:23]
	s_mov_b32 m0, s56
	v_lshl_add_u64 v[2:3], v[2:3], 0, s[26:27]
	v_mfma_f32_16x16x32_bf16 v[36:39], v[126:129], v[118:121], v[36:39]
	v_mfma_f32_16x16x32_bf16 v[44:47], v[130:133], v[118:121], v[44:47]
	v_mfma_f32_16x16x32_bf16 v[24:27], v[134:137], v[118:121], v[24:27]
	ds_read_b128 v[118:121], v18 offset:2048
	s_waitcnt lgkmcnt(0)
	v_mfma_f32_16x16x32_bf16 v[56:59], v[122:125], v[118:121], v[56:59]
	v_mfma_f32_16x16x32_bf16 v[60:63], v[126:129], v[118:121], v[60:63]
	v_mfma_f32_16x16x32_bf16 v[94:97], v[130:133], v[118:121], v[94:97]
	v_mfma_f32_16x16x32_bf16 v[52:55], v[134:137], v[118:121], v[52:55]
	ds_read_b128 v[118:121], v18 offset:4096
	s_waitcnt lgkmcnt(0)
	v_mfma_f32_16x16x32_bf16 v[106:109], v[122:125], v[118:121], v[106:109]
	v_mfma_f32_16x16x32_bf16 v[110:113], v[126:129], v[118:121], v[110:113]
	v_mfma_f32_16x16x32_bf16 v[114:117], v[130:133], v[118:121], v[114:117]
	v_mfma_f32_16x16x32_bf16 v[98:101], v[134:137], v[118:121], v[98:101]
	ds_read_b128 v[118:121], v18 offset:6144
	s_waitcnt lgkmcnt(0)
	v_mfma_f32_16x16x32_bf16 v[20:23], v[122:125], v[118:121], v[20:23]
	ds_read_b128 v[122:125], v19 offset:17408
	v_mfma_f32_16x16x32_bf16 v[32:35], v[126:129], v[118:121], v[32:35]
	ds_read_b128 v[126:129], v19 offset:19456
	v_mfma_f32_16x16x32_bf16 v[40:43], v[130:133], v[118:121], v[40:43]
	ds_read_b128 v[130:133], v19 offset:21504
	v_mfma_f32_16x16x32_bf16 v[48:51], v[134:137], v[118:121], v[48:51]
	ds_read_b128 v[134:137], v19 offset:23552
	ds_read_b128 v[118:121], v18 offset:1024
	s_waitcnt lgkmcnt(0)
	v_mfma_f32_16x16x32_bf16 v[28:31], v[122:125], v[118:121], v[28:31]
	v_mfma_f32_16x16x32_bf16 v[36:39], v[126:129], v[118:121], v[36:39]
	v_mfma_f32_16x16x32_bf16 v[44:47], v[130:133], v[118:121], v[44:47]
	v_mfma_f32_16x16x32_bf16 v[24:27], v[134:137], v[118:121], v[24:27]
	ds_read_b128 v[118:121], v18 offset:3072
	s_waitcnt lgkmcnt(0)
	v_mfma_f32_16x16x32_bf16 v[56:59], v[122:125], v[118:121], v[56:59]
	v_mfma_f32_16x16x32_bf16 v[60:63], v[126:129], v[118:121], v[60:63]
	v_mfma_f32_16x16x32_bf16 v[94:97], v[130:133], v[118:121], v[94:97]
	v_mfma_f32_16x16x32_bf16 v[52:55], v[134:137], v[118:121], v[52:55]
	ds_read_b128 v[118:121], v18 offset:5120
	s_waitcnt lgkmcnt(0)
	v_mfma_f32_16x16x32_bf16 v[106:109], v[122:125], v[118:121], v[106:109]
	v_mfma_f32_16x16x32_bf16 v[110:113], v[126:129], v[118:121], v[110:113]
	v_mfma_f32_16x16x32_bf16 v[114:117], v[130:133], v[118:121], v[114:117]
	v_mfma_f32_16x16x32_bf16 v[98:101], v[134:137], v[118:121], v[98:101]
	ds_read_b128 v[118:121], v18 offset:7168
	s_waitcnt vmcnt(0)
	s_waitcnt lgkmcnt(0)
	s_barrier
	global_load_lds_dwordx4 v[64:65], off
	v_lshl_add_u64 v[64:65], v[4:5], 0, s[22:23]
	s_mov_b32 m0, s57
	s_waitcnt lgkmcnt(0)
	v_mfma_f32_16x16x32_bf16 v[20:23], v[122:125], v[118:121], v[20:23]
	global_load_lds_dwordx4 v[64:65], off
	v_lshl_add_u64 v[64:65], v[6:7], 0, s[22:23]
	s_mov_b32 m0, s58
	v_mfma_f32_16x16x32_bf16 v[32:35], v[126:129], v[118:121], v[32:35]
	global_load_lds_dwordx4 v[64:65], off
	v_lshl_add_u64 v[64:65], v[8:9], 0, s[22:23]
	s_mov_b32 m0, s59
	v_mfma_f32_16x16x32_bf16 v[40:43], v[130:133], v[118:121], v[40:43]
	global_load_lds_dwordx4 v[64:65], off
	v_lshl_add_u64 v[64:65], v[10:11], 0, s[22:23]
	s_mov_b32 m0, s60
	v_mfma_f32_16x16x32_bf16 v[48:51], v[134:137], v[118:121], v[48:51]
	global_load_lds_dwordx4 v[64:65], off
	v_lshl_add_u64 v[64:65], v[12:13], 0, s[22:23]
	s_mov_b32 m0, s61
	s_nop 0
	global_load_lds_dwordx4 v[64:65], off
	v_lshl_add_u64 v[64:65], v[14:15], 0, s[22:23]
	s_mov_b32 m0, s97
	s_nop 0
	global_load_lds_dwordx4 v[64:65], off
	v_lshl_add_u64 v[64:65], v[16:17], 0, s[22:23]
	s_mov_b32 m0, s44
	s_mov_b32 s44, 7
	global_load_lds_dwordx4 v[64:65], off
	ds_read_b128 v[122:125], v19 offset:49152
	ds_read_b128 v[118:121], v18 offset:32768
	ds_read_b128 v[126:129], v19 offset:51200
	ds_read_b128 v[130:133], v19 offset:53248
	ds_read_b128 v[134:137], v19 offset:55296
	s_waitcnt lgkmcnt(0)
	v_mfma_f32_16x16x32_bf16 v[28:31], v[122:125], v[118:121], v[28:31]
	s_mov_b32 m0, s42
	v_mfma_f32_16x16x32_bf16 v[36:39], v[126:129], v[118:121], v[36:39]
	v_mfma_f32_16x16x32_bf16 v[44:47], v[130:133], v[118:121], v[44:47]
	v_mfma_f32_16x16x32_bf16 v[24:27], v[134:137], v[118:121], v[24:27]
	ds_read_b128 v[118:121], v18 offset:34816
	s_waitcnt lgkmcnt(0)
	v_mfma_f32_16x16x32_bf16 v[56:59], v[122:125], v[118:121], v[56:59]
	v_mfma_f32_16x16x32_bf16 v[60:63], v[126:129], v[118:121], v[60:63]
	v_mfma_f32_16x16x32_bf16 v[94:97], v[130:133], v[118:121], v[94:97]
	v_mfma_f32_16x16x32_bf16 v[52:55], v[134:137], v[118:121], v[52:55]
	ds_read_b128 v[118:121], v18 offset:36864
	s_waitcnt lgkmcnt(0)
	v_mfma_f32_16x16x32_bf16 v[106:109], v[122:125], v[118:121], v[106:109]
	v_mfma_f32_16x16x32_bf16 v[110:113], v[126:129], v[118:121], v[110:113]
	v_mfma_f32_16x16x32_bf16 v[114:117], v[130:133], v[118:121], v[114:117]
	v_mfma_f32_16x16x32_bf16 v[98:101], v[134:137], v[118:121], v[98:101]
	ds_read_b128 v[118:121], v18 offset:38912
	s_waitcnt lgkmcnt(0)
	v_mfma_f32_16x16x32_bf16 v[20:23], v[122:125], v[118:121], v[20:23]
	ds_read_b128 v[122:125], v19 offset:50176
	v_mfma_f32_16x16x32_bf16 v[32:35], v[126:129], v[118:121], v[32:35]
	ds_read_b128 v[126:129], v19 offset:52224
	v_mfma_f32_16x16x32_bf16 v[40:43], v[130:133], v[118:121], v[40:43]
	ds_read_b128 v[130:133], v19 offset:54272
	v_mfma_f32_16x16x32_bf16 v[48:51], v[134:137], v[118:121], v[48:51]
	ds_read_b128 v[134:137], v19 offset:56320
	ds_read_b128 v[118:121], v18 offset:33792
	s_waitcnt lgkmcnt(0)
	v_mfma_f32_16x16x32_bf16 v[28:31], v[122:125], v[118:121], v[28:31]
	v_mfma_f32_16x16x32_bf16 v[36:39], v[126:129], v[118:121], v[36:39]
	v_mfma_f32_16x16x32_bf16 v[44:47], v[130:133], v[118:121], v[44:47]
	v_mfma_f32_16x16x32_bf16 v[24:27], v[134:137], v[118:121], v[24:27]
	ds_read_b128 v[118:121], v18 offset:35840
	s_waitcnt lgkmcnt(0)
	v_mfma_f32_16x16x32_bf16 v[56:59], v[122:125], v[118:121], v[56:59]
	v_mfma_f32_16x16x32_bf16 v[60:63], v[126:129], v[118:121], v[60:63]
	v_mfma_f32_16x16x32_bf16 v[94:97], v[130:133], v[118:121], v[94:97]
	v_mfma_f32_16x16x32_bf16 v[52:55], v[134:137], v[118:121], v[52:55]
	ds_read_b128 v[118:121], v18 offset:37888
	s_waitcnt lgkmcnt(0)
	v_mfma_f32_16x16x32_bf16 v[106:109], v[122:125], v[118:121], v[106:109]
	v_mfma_f32_16x16x32_bf16 v[110:113], v[126:129], v[118:121], v[110:113]
	v_mfma_f32_16x16x32_bf16 v[114:117], v[130:133], v[118:121], v[114:117]
	v_mfma_f32_16x16x32_bf16 v[98:101], v[134:137], v[118:121], v[98:101]
	ds_read_b128 v[118:121], v18 offset:39936
	s_waitcnt vmcnt(0)
	s_waitcnt lgkmcnt(0)
	s_barrier
	global_load_lds_dwordx4 v[2:3], off
	v_lshl_add_u64 v[2:3], v[4:5], 0, s[26:27]
	s_mov_b32 m0, s43
	s_waitcnt lgkmcnt(0)
	v_mfma_f32_16x16x32_bf16 v[20:23], v[122:125], v[118:121], v[20:23]
	global_load_lds_dwordx4 v[2:3], off
	v_lshl_add_u64 v[2:3], v[6:7], 0, s[26:27]
	s_mov_b32 m0, s50
	v_mfma_f32_16x16x32_bf16 v[32:35], v[126:129], v[118:121], v[32:35]
	global_load_lds_dwordx4 v[2:3], off
	v_lshl_add_u64 v[2:3], v[8:9], 0, s[26:27]
	s_mov_b32 m0, s51
	v_mfma_f32_16x16x32_bf16 v[6:9], v[134:137], v[118:121], v[48:51]
	global_load_lds_dwordx4 v[2:3], off
	v_lshl_add_u64 v[2:3], v[10:11], 0, s[26:27]
	s_mov_b32 m0, s52
	v_mfma_f32_16x16x32_bf16 v[40:43], v[130:133], v[118:121], v[40:43]
	global_load_lds_dwordx4 v[2:3], off
	v_lshl_add_u64 v[2:3], v[12:13], 0, s[26:27]
	s_mov_b32 m0, s53
	s_mov_b32 s50, 0x40000
	global_load_lds_dwordx4 v[2:3], off
	v_lshl_add_u64 v[2:3], v[14:15], 0, s[26:27]
	s_mov_b32 m0, s54
	s_mov_b64 s[42:43], 0
	global_load_lds_dwordx4 v[2:3], off
	v_lshl_add_u64 v[2:3], v[16:17], 0, s[26:27]
	s_mov_b32 m0, s55
	s_movk_i32 s51, 0x200
	global_load_lds_dwordx4 v[2:3], off
	ds_read_b128 v[2:5], v19 offset:16384
	ds_read_b128 v[10:13], v18
	s_waitcnt lgkmcnt(0)
	v_mfma_f32_16x16x32_bf16 v[14:17], v[2:5], v[10:13], v[28:31]
	s_nop 2
	ds_read_b128 v[28:31], v19 offset:18432
	ds_read_b128 v[48:51], v19 offset:20480
	ds_read_b128 v[156:159], v19 offset:19456
	s_waitcnt lgkmcnt(0)
	v_mfma_f32_16x16x32_bf16 v[118:121], v[48:51], v[10:13], v[44:47]
	s_nop 2
	ds_read_b128 v[44:47], v19 offset:22528
	ds_read_b128 v[160:163], v19 offset:21504
	ds_read_b128 v[138:141], v19 offset:17408
	v_mfma_f32_16x16x32_bf16 v[36:39], v[28:31], v[10:13], v[36:39]
	s_waitcnt lgkmcnt(0)
	v_mfma_f32_16x16x32_bf16 v[10:13], v[44:47], v[10:13], v[24:27]
	s_nop 2
	ds_read_b128 v[24:27], v18 offset:2048
	s_waitcnt lgkmcnt(0)
	v_mfma_f32_16x16x32_bf16 v[122:125], v[2:5], v[24:27], v[56:59]
	v_mfma_f32_16x16x32_bf16 v[126:129], v[28:31], v[24:27], v[60:63]
	v_mfma_f32_16x16x32_bf16 v[94:97], v[48:51], v[24:27], v[94:97]
	v_mfma_f32_16x16x32_bf16 v[24:27], v[44:47], v[24:27], v[52:55]
	s_nop 2
	ds_read_b128 v[52:55], v18 offset:4096
	s_waitcnt lgkmcnt(0)
	v_mfma_f32_16x16x32_bf16 v[106:109], v[2:5], v[52:55], v[106:109]
	v_mfma_f32_16x16x32_bf16 v[110:113], v[28:31], v[52:55], v[110:113]
	v_mfma_f32_16x16x32_bf16 v[114:117], v[48:51], v[52:55], v[114:117]
	v_mfma_f32_16x16x32_bf16 v[98:101], v[44:47], v[52:55], v[98:101]
	ds_read_b128 v[52:55], v18 offset:6144
	s_waitcnt lgkmcnt(0)
	v_mfma_f32_16x16x32_bf16 v[152:155], v[44:47], v[52:55], v[6:9]
	s_nop 2
	ds_read_b128 v[6:9], v18 offset:1024
	s_waitcnt lgkmcnt(0)
	v_mfma_f32_16x16x32_bf16 v[58:61], v[160:163], v[6:9], v[118:121]
	s_nop 2
	ds_read_b128 v[118:121], v19 offset:23552
	v_mfma_f32_16x16x32_bf16 v[2:5], v[2:5], v[52:55], v[20:23]
	v_mfma_f32_16x16x32_bf16 v[130:133], v[28:31], v[52:55], v[32:35]
	v_mfma_f32_16x16x32_bf16 v[134:137], v[48:51], v[52:55], v[40:43]
	v_mfma_f32_16x16x32_bf16 v[46:49], v[138:141], v[6:9], v[14:17]
	v_mfma_f32_16x16x32_bf16 v[50:53], v[156:159], v[6:9], v[36:39]
	s_waitcnt lgkmcnt(0)
	v_mfma_f32_16x16x32_bf16 v[62:65], v[118:121], v[6:9], v[10:13]
	ds_read_b128 v[6:9], v18 offset:3072
	s_waitcnt lgkmcnt(0)
	v_mfma_f32_16x16x32_bf16 v[54:57], v[138:141], v[6:9], v[122:125]
	v_mfma_f32_16x16x32_bf16 v[34:37], v[156:159], v[6:9], v[126:129]
	v_mfma_f32_16x16x32_bf16 v[30:33], v[160:163], v[6:9], v[94:97]
	v_mfma_f32_16x16x32_bf16 v[22:25], v[118:121], v[6:9], v[24:27]
	ds_read_b128 v[6:9], v18 offset:5120
	s_nop 0
	v_lshl_add_u64 v[94:95], v[86:87], 0, s[2:3]
	v_lshl_add_u64 v[96:97], v[88:89], 0, s[2:3]
	s_waitcnt lgkmcnt(0)
	v_mfma_f32_16x16x32_bf16 v[38:41], v[138:141], v[6:9], v[106:109]
	s_nop 2
	ds_read_b128 v[106:109], v18 offset:7168
	v_mfma_f32_16x16x32_bf16 v[14:17], v[156:159], v[6:9], v[110:113]
	v_mfma_f32_16x16x32_bf16 v[10:13], v[160:163], v[6:9], v[114:117]
	v_mfma_f32_16x16x32_bf16 v[6:9], v[118:121], v[6:9], v[98:101]
	s_waitcnt lgkmcnt(0)
	v_mfma_f32_16x16x32_bf16 v[42:45], v[138:141], v[106:109], v[2:5]
	s_nop 0
	v_lshl_add_u64 v[98:99], v[90:91], 0, s[2:3]
	v_lshl_add_u64 v[100:101], v[92:93], 0, s[2:3]
	v_mfma_f32_16x16x32_bf16 v[18:21], v[156:159], v[106:109], v[130:133]
	v_mfma_f32_16x16x32_bf16 v[26:29], v[160:163], v[106:109], v[134:137]
	v_mfma_f32_16x16x32_bf16 v[2:5], v[118:121], v[106:109], v[152:155]
	s_branch .LBB0_63
	s_branch .LBB0_62
	.p2align 8

.LBB0_299:
	s_lshl_b32 s40, s12, 7
	s_ashr_i32 s41, s40, 31
	s_lshl_b32 s0, s56, 7
	s_lshl_b64 s[42:43], s[40:41], 11
	s_add_u32 s44, s24, s42
	s_addc_u32 s45, s25, s43
	s_ashr_i32 s1, s0, 31
	s_lshl_b64 s[48:49], s[0:1], 11
	s_add_u32 s50, s5, s48
	v_readfirstlane_b32 s1, v67
	v_add_u32_e32 v4, 0x4000, v67
	s_waitcnt lgkmcnt(0)
	s_barrier
	s_addc_u32 s51, s96, s49
	v_lshl_add_u64 v[2:3], s[44:45], 0, v[92:93]
	s_mov_b32 m0, s1
	v_readfirstlane_b32 s1, v4
	v_add_u32_e32 v4, 0x1000, v67
	global_load_lds_dwordx4 v[2:3], off
	v_lshl_add_u64 v[2:3], s[50:51], 0, v[92:93]
	s_mov_b32 m0, s1
	v_readfirstlane_b32 s1, v4
	v_add_u32_e32 v4, 0x5000, v67
	global_load_lds_dwordx4 v[2:3], off
	v_lshl_add_u64 v[2:3], s[44:45], 0, v[94:95]
	s_mov_b32 m0, s1
	v_readfirstlane_b32 s1, v4
	v_add_u32_e32 v4, 0x2000, v67
	global_load_lds_dwordx4 v[2:3], off
	v_lshl_add_u64 v[2:3], s[50:51], 0, v[94:95]
	s_mov_b32 m0, s1
	v_readfirstlane_b32 s1, v4
	v_add_u32_e32 v4, 0x6000, v67
	global_load_lds_dwordx4 v[2:3], off
	v_lshl_add_u64 v[2:3], s[44:45], 0, v[96:97]
	s_mov_b32 m0, s1
	v_readfirstlane_b32 s1, v4
	v_add_u32_e32 v4, 0x3000, v67
	global_load_lds_dwordx4 v[2:3], off
	v_lshl_add_u64 v[2:3], s[50:51], 0, v[96:97]
	s_mov_b32 m0, s1
	v_readfirstlane_b32 s1, v4
	v_add_u32_e32 v4, 0x7000, v67
	global_load_lds_dwordx4 v[2:3], off
	v_lshl_add_u64 v[2:3], s[44:45], 0, v[98:99]
	s_mov_b32 m0, s1
	v_readfirstlane_b32 s1, v4
	global_load_lds_dwordx4 v[2:3], off
	v_lshl_add_u64 v[2:3], s[50:51], 0, v[98:99]
	s_mov_b32 m0, s1
	v_lshl_add_u64 v[100:101], v[76:77], 0, s[42:43]
	global_load_lds_dwordx4 v[2:3], off
	v_mov_b32_e32 v2, 0
	v_lshl_add_u64 v[102:103], v[78:79], 0, s[42:43]
	v_lshl_add_u64 v[104:105], v[80:81], 0, s[42:43]
	v_lshl_add_u64 v[106:107], v[82:83], 0, s[42:43]
	v_lshl_add_u64 v[108:109], v[84:85], 0, s[48:49]
	v_lshl_add_u64 v[110:111], v[86:87], 0, s[48:49]
	v_lshl_add_u64 v[112:113], v[88:89], 0, s[48:49]
	v_lshl_add_u64 v[114:115], v[90:91], 0, s[48:49]
	s_mov_b32 s13, 0
	s_mov_b64 s[42:43], 0
	v_mov_b32_e32 v3, v2
	v_mov_b32_e32 v4, v2
	v_mov_b32_e32 v5, v2
	v_mov_b32_e32 v6, v2
	v_mov_b32_e32 v7, v2
	v_mov_b32_e32 v8, v2
	v_mov_b32_e32 v9, v2
	v_mov_b32_e32 v10, v2
	v_mov_b32_e32 v11, v2
	v_mov_b32_e32 v12, v2
	v_mov_b32_e32 v13, v2
	v_mov_b32_e32 v14, v2
	v_mov_b32_e32 v15, v2
	v_mov_b32_e32 v16, v2
	v_mov_b32_e32 v17, v2
	v_mov_b32_e32 v18, v2
	v_mov_b32_e32 v19, v2
	v_mov_b32_e32 v20, v2
	v_mov_b32_e32 v21, v2
	v_mov_b32_e32 v22, v2
	v_mov_b32_e32 v23, v2
	v_mov_b32_e32 v24, v2
	v_mov_b32_e32 v25, v2
	v_mov_b32_e32 v26, v2
	v_mov_b32_e32 v27, v2
	v_mov_b32_e32 v28, v2
	v_mov_b32_e32 v29, v2
	v_mov_b32_e32 v30, v2
	v_mov_b32_e32 v31, v2
	v_mov_b32_e32 v32, v2
	v_mov_b32_e32 v33, v2
	v_mov_b32_e32 v34, v2
	v_mov_b32_e32 v35, v2
	v_mov_b32_e32 v36, v2
	v_mov_b32_e32 v37, v2
	v_mov_b32_e32 v38, v2
	v_mov_b32_e32 v39, v2
	v_mov_b32_e32 v40, v2
	v_mov_b32_e32 v41, v2
	v_mov_b32_e32 v42, v2
	v_mov_b32_e32 v43, v2
	v_mov_b32_e32 v44, v2
	v_mov_b32_e32 v45, v2
	v_mov_b32_e32 v46, v2
	v_mov_b32_e32 v47, v2
	v_mov_b32_e32 v48, v2
	v_mov_b32_e32 v49, v2
	v_mov_b32_e32 v50, v2
	v_mov_b32_e32 v51, v2
	v_mov_b32_e32 v52, v2
	v_mov_b32_e32 v53, v2
	v_mov_b32_e32 v54, v2
	v_mov_b32_e32 v55, v2
	v_mov_b32_e32 v56, v2
	v_mov_b32_e32 v57, v2
	v_mov_b32_e32 v58, v2
	v_mov_b32_e32 v59, v2
	v_mov_b32_e32 v60, v2
	v_mov_b32_e32 v61, v2
	v_mov_b32_e32 v62, v2
	v_mov_b32_e32 v63, v2
	v_mov_b32_e32 v64, v2
	v_mov_b32_e32 v65, v2
	s_branch .LBB0_300
	.p2align 8
